# spatial gating: LayerNorm gain/bias quads prefetched with the v tile (spare VGPRs) instead of four serialized load rounds
# speedup vs baseline: 1.0210x; 1.0036x over previous
; __device__ __forceinline__ void sg_unit(LAS unsigned char* lds, const bf16_t* P0, bf16_t* MIX, const float* lng, const float* lnb, const float* wsp, const float* bsp, int b, int nch, int g) {
;     ...
;     __syncthreads();
;     {
;         const int s = tid >> 2, part = tid & 3;
;         const bf16_t* vp = P0 + (rowbase + s) * AB_IN + 512 + 128 * g + 32 * part;
;         float x[32]; float sum = 0.f;
; #pragma unroll
;         for (int j = 0; j < 4; ++j) { const u32x4 wv = *(const u32x4*)(vp + 8 * j);
;             x[8 * j + 0] = bflo(wv.x); x[8 * j + 1] = bfhi(wv.x); x[8 * j + 2] = bflo(wv.y); x[8 * j + 3] = bfhi(wv.y);
;             x[8 * j + 4] = bflo(wv.z); x[8 * j + 5] = bfhi(wv.z); x[8 * j + 6] = bflo(wv.w); x[8 * j + 7] = bfhi(wv.w); }
; #pragma unroll
;         for (int j = 0; j < 32; ++j) sum += x[j];
;         sum += __shfl_xor(sum, 1); sum += __shfl_xor(sum, 2);
;         const float mean = sum * (1.f / 128.f); float q = 0.f;
; #pragma unroll
;         for (int j = 0; j < 32; ++j) { x[j] -= mean; q += x[j] * x[j]; }
;         q += __shfl_xor(q, 1); q += __shfl_xor(q, 2);
;         const float rstd = __builtin_amdgcn_rsqf(q * (1.f / 128.f) + LN_EPS);
;         const float* gp = lng + 128 * g + 32 * part; const float* bp = lnb + 128 * g + 32 * part;
.LBB0_290:
	s_cmpk_gt_i32 s33, 0x7ff
	s_mov_b64 s[0:1], -1
	s_cbranch_scc0 .LBB0_294
	s_lshl_b32 s1, s33, 5
	s_and_b32 s5, s1, 0x7fffff80
	s_add_i32 s5, s5, 0xffff0000
	v_add_u32_e32 v0, s5, v81
	s_and_b32 s0, s33, 3
	v_mul_lo_u32 v72, v0, s3
	v_lshl_add_u64 v[0:1], s[26:27], 0, v[72:73]
	s_lshl_b32 s22, s0, 8
	v_lshl_add_u64 v[0:1], v[0:1], 0, s[22:23]
	v_mov_b32_e32 v91, v73
	s_waitcnt vmcnt(7)
	v_lshl_add_u64 v[12:13], v[0:1], 0, v[90:91]
	s_barrier
	global_load_dwordx4 v[0:3], v[12:13], off offset:1072
	global_load_dwordx4 v[4:7], v[12:13], off offset:1056
	global_load_dwordx4 v[8:11], v[12:13], off offset:1040
	s_nop 0
	global_load_dwordx4 v[12:15], v[12:13], off offset:1024
	v_cmp_lt_i32_e32 vcc, v113, v114
	s_lshl_b32 s22, s0, 9
	v_lshl_add_u64 v[148:149], v[74:75], 0, s[22:23]
	v_lshl_add_u64 v[218:219], v[76:77], 0, s[22:23]
	global_load_dwordx4 v[150:153], v[148:149], off offset:16
	global_load_dwordx4 v[154:157], v[148:149], off
	global_load_dwordx4 v[158:161], v[218:219], off offset:16
	global_load_dwordx4 v[162:165], v[218:219], off
	global_load_dwordx4 v[166:169], v[148:149], off offset:48
	global_load_dwordx4 v[170:173], v[148:149], off offset:32
	global_load_dwordx4 v[178:181], v[218:219], off offset:48
	global_load_dwordx4 v[182:185], v[218:219], off offset:32
	global_load_dwordx4 v[186:189], v[148:149], off offset:80
	global_load_dwordx4 v[190:193], v[148:149], off offset:64
	global_load_dwordx4 v[194:197], v[218:219], off offset:80
	global_load_dwordx4 v[198:201], v[218:219], off offset:64
	global_load_dwordx4 v[202:205], v[148:149], off offset:112
	global_load_dwordx4 v[206:209], v[148:149], off offset:96
	global_load_dwordx4 v[210:213], v[218:219], off offset:112
	global_load_dwordx4 v[214:217], v[218:219], off offset:96
	s_lshl_b32 s4, s0, 7
	s_lshl_b32 s0, s0, 14
	v_add_lshl_u32 v72, s0, v83, 2
	v_readlane_b32 s0, v254, 18
	v_readlane_b32 s1, v254, 19
	s_waitcnt vmcnt(18)
	v_lshlrev_b32_e32 v24, 16, v4
	s_waitcnt vmcnt(17)
	v_lshlrev_b32_e32 v32, 16, v8
	s_waitcnt vmcnt(16)
	v_lshlrev_b32_e32 v40, 16, v12
	v_and_b32_e32 v39, 0xffff0000, v12
	v_lshlrev_b32_e32 v36, 16, v14
	v_and_b32_e32 v35, 0xffff0000, v14
	v_lshlrev_b32_e32 v34, 16, v15
	v_and_b32_e32 v33, 0xffff0000, v15
	v_lshlrev_b32_e32 v15, 16, v0
	v_and_b32_e32 v14, 0xffff0000, v0
	v_add_f32_e32 v0, 0, v40
	v_lshlrev_b32_e32 v38, 16, v13
	v_add_f32_e32 v0, v0, v39
	v_and_b32_e32 v37, 0xffff0000, v13
	v_add_f32_e32 v0, v0, v38
	v_add_f32_e32 v0, v0, v37
	v_add_f32_e32 v0, v0, v36
	v_add_f32_e32 v0, v0, v35
	v_add_f32_e32 v0, v0, v34
	v_add_f32_e32 v0, v0, v33
	v_and_b32_e32 v31, 0xffff0000, v8
	v_add_f32_e32 v0, v0, v32
	v_lshlrev_b32_e32 v30, 16, v9
	v_add_f32_e32 v0, v0, v31
	v_and_b32_e32 v29, 0xffff0000, v9
	v_add_f32_e32 v0, v0, v30
	v_lshlrev_b32_e32 v28, 16, v10
	v_add_f32_e32 v0, v0, v29
	v_and_b32_e32 v27, 0xffff0000, v10
	v_add_f32_e32 v0, v0, v28
	v_lshlrev_b32_e32 v26, 16, v11
	v_add_f32_e32 v0, v0, v27
	v_and_b32_e32 v25, 0xffff0000, v11
	v_add_f32_e32 v0, v0, v26
	v_add_f32_e32 v0, v0, v25
	v_and_b32_e32 v22, 0xffff0000, v4
	v_add_f32_e32 v0, v0, v24
	v_lshlrev_b32_e32 v21, 16, v5
	v_add_f32_e32 v0, v0, v22
	v_and_b32_e32 v20, 0xffff0000, v5
	v_add_f32_e32 v0, v0, v21
	v_lshlrev_b32_e32 v19, 16, v6
	v_add_f32_e32 v0, v0, v20
	v_and_b32_e32 v18, 0xffff0000, v6
	v_add_f32_e32 v0, v0, v19
	v_lshlrev_b32_e32 v17, 16, v7
	v_add_f32_e32 v0, v0, v18
	v_and_b32_e32 v16, 0xffff0000, v7
	v_add_f32_e32 v0, v0, v17
	v_add_f32_e32 v0, v0, v16
	v_add_f32_e32 v0, v0, v15
	v_lshlrev_b32_e32 v13, 16, v1
	v_add_f32_e32 v0, v0, v14
	v_and_b32_e32 v12, 0xffff0000, v1
	v_add_f32_e32 v0, v0, v13
	v_lshlrev_b32_e32 v11, 16, v2
	v_add_f32_e32 v0, v0, v12
	v_and_b32_e32 v10, 0xffff0000, v2
	v_add_f32_e32 v0, v0, v11
	v_add_f32_e32 v2, v0, v10
	v_cndmask_b32_e32 v0, v112, v113, vcc
	v_cmp_lt_i32_e32 vcc, v115, v114
	v_lshlrev_b32_e32 v6, 2, v0
	v_lshlrev_b32_e32 v1, 16, v3
	v_cndmask_b32_e32 v0, v112, v115, vcc
	v_lshlrev_b32_e32 v7, 2, v0
	v_and_b32_e32 v0, 0xffff0000, v3
	v_add_f32_e32 v2, v2, v1
	v_add_f32_e32 v2, v2, v0
	ds_bpermute_b32 v3, v6, v2
	s_waitcnt lgkmcnt(0)
	v_add_f32_e32 v2, v2, v3
	ds_bpermute_b32 v3, v7, v2
	s_waitcnt lgkmcnt(0)
	v_add_f32_e32 v3, v2, v3
	v_fmac_f32_e32 v39, 0xbc000000, v3
	v_fmac_f32_e32 v40, 0xbc000000, v3
	v_mul_f32_e32 v8, v39, v39
	v_fmac_f32_e32 v8, v40, v40
	v_fmac_f32_e32 v38, 0xbc000000, v3
	v_fmac_f32_e32 v8, v38, v38
	v_fmac_f32_e32 v37, 0xbc000000, v3
	v_fmac_f32_e32 v8, v37, v37
	v_fmac_f32_e32 v36, 0xbc000000, v3
	v_fmac_f32_e32 v8, v36, v36
	v_fmac_f32_e32 v35, 0xbc000000, v3
	v_fmac_f32_e32 v8, v35, v35
	v_fmac_f32_e32 v34, 0xbc000000, v3
	v_fmac_f32_e32 v8, v34, v34
	v_fmac_f32_e32 v33, 0xbc000000, v3
	v_fmac_f32_e32 v8, v33, v33
	v_fmac_f32_e32 v32, 0xbc000000, v3
	v_fmac_f32_e32 v8, v32, v32
	v_fmac_f32_e32 v31, 0xbc000000, v3
	v_fmac_f32_e32 v8, v31, v31
	v_fmac_f32_e32 v30, 0xbc000000, v3
	v_fmac_f32_e32 v8, v30, v30
	v_fmac_f32_e32 v29, 0xbc000000, v3
	v_fmac_f32_e32 v8, v29, v29
	v_fmac_f32_e32 v28, 0xbc000000, v3
	v_fmac_f32_e32 v8, v28, v28
	v_fmac_f32_e32 v27, 0xbc000000, v3
	v_fmac_f32_e32 v8, v27, v27
	v_fmac_f32_e32 v26, 0xbc000000, v3
	v_fmac_f32_e32 v8, v26, v26
	v_fmac_f32_e32 v25, 0xbc000000, v3
	v_fmac_f32_e32 v8, v25, v25
	v_fmac_f32_e32 v24, 0xbc000000, v3
	v_fmac_f32_e32 v8, v24, v24
	v_fmac_f32_e32 v22, 0xbc000000, v3
	v_fmac_f32_e32 v8, v22, v22
	v_fmac_f32_e32 v21, 0xbc000000, v3
	v_fmac_f32_e32 v8, v21, v21
	v_fmac_f32_e32 v20, 0xbc000000, v3
	v_fmac_f32_e32 v8, v20, v20
	v_fmac_f32_e32 v19, 0xbc000000, v3
	v_fmac_f32_e32 v8, v19, v19
	v_fmac_f32_e32 v18, 0xbc000000, v3
	v_fmac_f32_e32 v8, v18, v18
	v_fmac_f32_e32 v17, 0xbc000000, v3
	v_fmac_f32_e32 v8, v17, v17
	v_fmac_f32_e32 v16, 0xbc000000, v3
	v_fmac_f32_e32 v8, v16, v16
	v_fmac_f32_e32 v15, 0xbc000000, v3
	v_fmac_f32_e32 v8, v15, v15
	v_fmac_f32_e32 v14, 0xbc000000, v3
	v_fmac_f32_e32 v8, v14, v14
	v_fmac_f32_e32 v13, 0xbc000000, v3
	v_fmac_f32_e32 v8, v13, v13
	v_fmac_f32_e32 v12, 0xbc000000, v3
	v_mul_f32_e32 v2, 0x3c000000, v3
	v_fmac_f32_e32 v8, v12, v12
	v_fmac_f32_e32 v11, 0xbc000000, v3
	v_fmac_f32_e32 v8, v11, v11
	v_fmac_f32_e32 v10, 0xbc000000, v3
	v_pk_add_f32 v[4:5], v[0:1], v[2:3] op_sel_hi:[1,0] neg_lo:[0,1] neg_hi:[0,1]
	v_fmac_f32_e32 v8, v10, v10
	v_pk_mul_f32 v[0:1], v[4:5], v[4:5]
	s_nop 0
	v_add_f32_e32 v1, v1, v8
	v_add_f32_e32 v0, v0, v1
	ds_bpermute_b32 v1, v6, v0
	v_lshl_add_u64 v[8:9], v[74:75], 0, s[22:23]
	s_waitcnt lgkmcnt(0)
; #define LAS __attribute__((address_space(3)))
; __device__ __forceinline__ unsigned pk2(float lo, float hi) { unsigned r; asm("v_cvt_pk_bf16_f32 %0, %1, %2" : "=v"(r) : "v"(lo), "v"(hi)); return r; }
; __device__ __forceinline__ void sg_unit(LAS unsigned char* lds, const bf16_t* P0, bf16_t* MIX, const float* lng, const float* lnb, const float* wsp, const float* bsp, int b, int nch, int g) {
;     ...
;         const float rstd = __builtin_amdgcn_rsqf(q * (1.f / 128.f) + LN_EPS);
;         const float* gp = lng + 128 * g + 32 * part; const float* bp = lnb + 128 * g + 32 * part;
; #pragma unroll
;         for (int j = 0; j < 4; ++j) { float y[8];
; #pragma unroll
;             for (int e = 0; e < 8; ++e) y[e] = x[8 * j + e] * rstd * gp[8 * j + e] + bp[8 * j + e];
;             *(LAS u32x4*)(vnl + s * 136 + 32 * part + 8 * j) = (u32x4){pk2(y[0], y[1]), pk2(y[2], y[3]), pk2(y[4], y[5]), pk2(y[6], y[7])}; }
	v_add_f32_e32 v0, v0, v1
	ds_bpermute_b32 v1, v7, v0
	v_lshl_add_u64 v[6:7], v[76:77], 0, s[22:23]
	s_waitcnt lgkmcnt(0)
	v_add_f32_e32 v0, v0, v1
	v_fmamk_f32 v0, v0, 0x3c000000, v106
	v_rsq_f32_e32 v23, v0
	s_nop 0
	v_mul_f32_e32 v52, v40, v23
	s_waitcnt vmcnt(0)
	v_mov_b32_e32 v0, v150
	v_mov_b32_e32 v1, v151
	v_mov_b32_e32 v2, v152
	v_mov_b32_e32 v3, v153
	v_mov_b32_e32 v40, v154
	v_mov_b32_e32 v41, v155
	v_mov_b32_e32 v42, v156
	v_mov_b32_e32 v43, v157
	v_mov_b32_e32 v44, v158
	v_mov_b32_e32 v45, v159
	v_mov_b32_e32 v46, v160
	v_mov_b32_e32 v47, v161
	v_mov_b32_e32 v48, v162
	v_mov_b32_e32 v49, v163
	v_mov_b32_e32 v50, v164
	v_mov_b32_e32 v51, v165
	v_mul_f32_e32 v36, v36, v23
	v_mul_f32_e32 v39, v39, v23
	v_mul_f32_e32 v38, v38, v23
	v_mul_f32_e32 v37, v37, v23
	v_mul_f32_e32 v28, v28, v23
	v_mul_f32_e32 v31, v31, v23
	v_mul_f32_e32 v30, v30, v23
	v_mul_f32_e32 v29, v29, v23
	v_mul_f32_e32 v19, v19, v23
	v_mul_f32_e32 v22, v22, v23
	v_mul_f32_e32 v21, v21, v23
	v_mul_f32_e32 v20, v20, v23
	v_mul_f32_e32 v11, v11, v23
	v_mul_f32_e32 v15, v15, v23
	v_mul_f32_e32 v14, v14, v23
	v_mul_f32_e32 v13, v13, v23
	v_mul_f32_e32 v12, v12, v23
	s_waitcnt vmcnt(1)
	v_fma_f32 v36, v0, v36, v44
	v_mul_f32_e32 v0, v35, v23
	v_fma_f32 v35, v1, v0, v45
	v_mul_f32_e32 v0, v34, v23
	v_fma_f32 v34, v2, v0, v46
	v_mul_f32_e32 v0, v33, v23
	s_waitcnt vmcnt(0)
	v_fma_f32 v40, v40, v52, v48
	v_fma_f32 v39, v41, v39, v49
	v_fma_f32 v38, v42, v38, v50
	v_fmac_f32_e32 v51, v43, v37
	v_fmac_f32_e32 v47, v3, v0
	v_cvt_pk_bf16_f32 v0, v40, v39
	v_cvt_pk_bf16_f32 v1, v38, v51
	v_cvt_pk_bf16_f32 v2, v36, v35
	v_cvt_pk_bf16_f32 v3, v34, v47
	ds_write_b128 v107, v[0:3]
	v_mul_f32_e32 v44, v32, v23
	v_mov_b32_e32 v0, v166
	v_mov_b32_e32 v1, v167
	v_mov_b32_e32 v2, v168
	v_mov_b32_e32 v3, v169
	v_mov_b32_e32 v32, v170
	v_mov_b32_e32 v33, v171
	v_mov_b32_e32 v34, v172
	v_mov_b32_e32 v35, v173
	v_mov_b32_e32 v36, v178
	v_mov_b32_e32 v37, v179
	v_mov_b32_e32 v38, v180
	v_mov_b32_e32 v39, v181
	v_mov_b32_e32 v40, v182
	v_mov_b32_e32 v41, v183
	v_mov_b32_e32 v42, v184
	v_mov_b32_e32 v43, v185
	s_waitcnt vmcnt(1)
	v_fma_f32 v28, v0, v28, v36
	v_mul_f32_e32 v0, v27, v23
	v_fma_f32 v27, v1, v0, v37
	v_mul_f32_e32 v0, v26, v23
	v_fma_f32 v26, v2, v0, v38
	v_mul_f32_e32 v0, v25, v23
	s_waitcnt vmcnt(0)
	v_fma_f32 v32, v32, v44, v40
	v_fma_f32 v31, v33, v31, v41
	v_fma_f32 v30, v34, v30, v42
	v_fmac_f32_e32 v43, v35, v29
	v_fmac_f32_e32 v39, v3, v0
	v_cvt_pk_bf16_f32 v0, v32, v31
	v_cvt_pk_bf16_f32 v1, v30, v43
	v_cvt_pk_bf16_f32 v2, v28, v27
	v_cvt_pk_bf16_f32 v3, v26, v39
	ds_write_b128 v107, v[0:3] offset:16
	v_mul_f32_e32 v36, v24, v23
	v_mov_b32_e32 v0, v186
	v_mov_b32_e32 v1, v187
	v_mov_b32_e32 v2, v188
	v_mov_b32_e32 v3, v189
	v_mov_b32_e32 v24, v190
	v_mov_b32_e32 v25, v191
	v_mov_b32_e32 v26, v192
	v_mov_b32_e32 v27, v193
	v_mov_b32_e32 v28, v194
	v_mov_b32_e32 v29, v195
	v_mov_b32_e32 v30, v196
	v_mov_b32_e32 v31, v197
	v_mov_b32_e32 v32, v198
	v_mov_b32_e32 v33, v199
	v_mov_b32_e32 v34, v200
	v_mov_b32_e32 v35, v201
	s_waitcnt vmcnt(1)
	v_fma_f32 v19, v0, v19, v28
	v_mul_f32_e32 v0, v18, v23
	v_fma_f32 v18, v1, v0, v29
	v_mul_f32_e32 v0, v17, v23
	v_fma_f32 v17, v2, v0, v30
	v_mul_f32_e32 v0, v16, v23
	s_waitcnt vmcnt(0)
	v_fma_f32 v24, v24, v36, v32
	v_fma_f32 v22, v25, v22, v33
	v_fma_f32 v21, v26, v21, v34
	v_fmac_f32_e32 v35, v27, v20
	v_fmac_f32_e32 v31, v3, v0
	v_cvt_pk_bf16_f32 v0, v24, v22
	v_cvt_pk_bf16_f32 v1, v21, v35
	v_cvt_pk_bf16_f32 v2, v19, v18
	v_cvt_pk_bf16_f32 v3, v17, v31
	ds_write_b128 v107, v[0:3] offset:32
	v_mov_b32_e32 v0, v202
	v_mov_b32_e32 v1, v203
	v_mov_b32_e32 v2, v204
	v_mov_b32_e32 v3, v205
	v_mov_b32_e32 v16, v206
	v_mov_b32_e32 v17, v207
	v_mov_b32_e32 v18, v208
	v_mov_b32_e32 v19, v209
	v_mov_b32_e32 v24, v210
	v_mov_b32_e32 v25, v211
	v_mov_b32_e32 v26, v212
	v_mov_b32_e32 v27, v213
	s_nop 0
	v_mov_b32_e32 v6, v214
	v_mov_b32_e32 v7, v215
	v_mov_b32_e32 v8, v216
	v_mov_b32_e32 v9, v217
	v_mov_b32_e32 v32, v105
	v_mov_b32_e32 v33, v104
	v_mov_b32_e32 v34, v103
	s_waitcnt vmcnt(1)
	v_fma_f32 v11, v11, v0, v24
	v_mul_f32_e32 v0, v10, v23
	v_fma_f32 v10, v0, v1, v25
	v_mul_f32_e32 v0, v5, v23
	v_fma_f32 v5, v0, v2, v26
	v_mul_f32_e32 v0, v4, v23
	s_waitcnt vmcnt(0)
	v_fma_f32 v6, v16, v15, v6
	v_fma_f32 v7, v17, v14, v7
	v_fma_f32 v8, v18, v13, v8
	v_fmac_f32_e32 v9, v12, v19
	v_fmac_f32_e32 v27, v0, v3
	v_cvt_pk_bf16_f32 v0, v6, v7
	v_cvt_pk_bf16_f32 v1, v8, v9
	v_cvt_pk_bf16_f32 v2, v11, v10
	v_cvt_pk_bf16_f32 v3, v5, v27
	ds_write_b128 v107, v[0:3] offset:48
	v_readlane_b32 s98, v254, 8
	s_nop 0
	s_and_b32 s99, s98, 3
	s_sub_i32 s98, s33, s98
	s_cmp_lg_u32 s99, 0
	s_cbranch_scc1 .Lsg_stage_w
	s_cmpk_gt_i32 s98, 0x7ff
	s_cbranch_scc1 .Lsg_skip_w
